# v27 plus full-line stores for the K-split partial tiles of the residual GEMM
# baseline (speedup 1.0000x reference)
.Lepi_r_split:
	s_lshl_b32 s3, s65, 8
	s_ashr_i32 s85, s84, 31
	s_add_i32 s30, s3, 0xffffc000
	s_ashr_i32 s31, s30, 31
	s_lshl_b64 s[34:35], s[84:85], 22
	s_add_u32 s3, s93, s34
	s_addc_u32 s24, s53, s35
	s_lshl_b64 s[30:31], s[30:31], 12
	s_add_u32 s30, s3, s30
	s_addc_u32 s31, s24, s31
	s_waitcnt vmcnt(0)
	v_mul_f32_e32 v132, s88, v132
	v_mul_f32_e32 v133, s88, v133
	v_mul_f32_e32 v134, s88, v134
	v_mul_f32_e32 v135, s88, v135
	v_mul_f32_e32 v136, s88, v136
	v_mul_f32_e32 v137, s88, v137
	v_mul_f32_e32 v138, s88, v138
	v_mul_f32_e32 v139, s88, v139
	v_mul_f32_e32 v140, s88, v140
	v_mul_f32_e32 v141, s88, v141
	v_mul_f32_e32 v142, s88, v142
	v_mul_f32_e32 v143, s88, v143
	v_mul_f32_e32 v168, s88, v168
	v_mul_f32_e32 v169, s88, v169
	v_mul_f32_e32 v170, s88, v170
	v_mul_f32_e32 v171, s88, v171
	v_cmp_gt_u32_e32 vcc, 8, v164
	v_cndmask_b32_e32 v132, v136, v132, vcc
	v_cndmask_b32_e32 v133, v137, v133, vcc
	v_cndmask_b32_e32 v134, v138, v134, vcc
	v_cndmask_b32_e32 v135, v139, v135, vcc
	v_cndmask_b32_e32 v140, v168, v140, vcc
	v_cndmask_b32_e32 v141, v169, v141, vcc
	v_cndmask_b32_e32 v142, v170, v142, vcc
	v_cndmask_b32_e32 v143, v171, v143, vcc
	v_cndmask_b32_dpp v232, v124, v128, vcc row_ror:8 row_mask:0xf bank_mask:0xf
	v_cndmask_b32_dpp v233, v125, v129, vcc row_ror:8 row_mask:0xf bank_mask:0xf
	v_cndmask_b32_dpp v234, v126, v130, vcc row_ror:8 row_mask:0xf bank_mask:0xf
	v_cndmask_b32_dpp v235, v127, v131, vcc row_ror:8 row_mask:0xf bank_mask:0xf
	s_not_b64 vcc, vcc
	v_cndmask_b32_dpp v124, v128, v124, vcc row_ror:8 row_mask:0xf bank_mask:0xf
	v_cndmask_b32_dpp v125, v129, v125, vcc row_ror:8 row_mask:0xf bank_mask:0xf
	v_cndmask_b32_dpp v126, v130, v126, vcc row_ror:8 row_mask:0xf bank_mask:0xf
	v_cndmask_b32_dpp v127, v131, v127, vcc row_ror:8 row_mask:0xf bank_mask:0xf
	s_not_b64 vcc, vcc
	v_pk_mul_f32 v[128:129], v[132:133], v[232:233]
	v_pk_mul_f32 v[130:131], v[134:135], v[234:235]
	v_pk_mul_f32 v[124:125], v[132:133], v[124:125]
	v_pk_mul_f32 v[126:127], v[134:135], v[126:127]
	global_store_dwordx4 v162, v[128:131], s[30:31]
	global_store_dwordx4 v163, v[124:127], s[30:31]
	v_cndmask_b32_dpp v232, v116, v120, vcc row_ror:8 row_mask:0xf bank_mask:0xf
	v_cndmask_b32_dpp v233, v117, v121, vcc row_ror:8 row_mask:0xf bank_mask:0xf
	v_cndmask_b32_dpp v234, v118, v122, vcc row_ror:8 row_mask:0xf bank_mask:0xf
	v_cndmask_b32_dpp v235, v119, v123, vcc row_ror:8 row_mask:0xf bank_mask:0xf
	s_not_b64 vcc, vcc
	v_cndmask_b32_dpp v116, v120, v116, vcc row_ror:8 row_mask:0xf bank_mask:0xf
	v_cndmask_b32_dpp v117, v121, v117, vcc row_ror:8 row_mask:0xf bank_mask:0xf
	v_cndmask_b32_dpp v118, v122, v118, vcc row_ror:8 row_mask:0xf bank_mask:0xf
	v_cndmask_b32_dpp v119, v123, v119, vcc row_ror:8 row_mask:0xf bank_mask:0xf
	s_not_b64 vcc, vcc
	v_pk_mul_f32 v[120:121], v[140:141], v[232:233]
	v_pk_mul_f32 v[122:123], v[142:143], v[234:235]
	v_pk_mul_f32 v[116:117], v[140:141], v[116:117]
	v_pk_mul_f32 v[118:119], v[142:143], v[118:119]
	global_store_dwordx4 v162, v[120:123], s[30:31] offset:512
	global_store_dwordx4 v163, v[116:119], s[30:31] offset:512
	s_add_u32 s30, s30, 0x10000
	s_addc_u32 s31, s31, 0
	v_cndmask_b32_dpp v232, v108, v112, vcc row_ror:8 row_mask:0xf bank_mask:0xf
	v_cndmask_b32_dpp v233, v109, v113, vcc row_ror:8 row_mask:0xf bank_mask:0xf
	v_cndmask_b32_dpp v234, v110, v114, vcc row_ror:8 row_mask:0xf bank_mask:0xf
	v_cndmask_b32_dpp v235, v111, v115, vcc row_ror:8 row_mask:0xf bank_mask:0xf
	s_not_b64 vcc, vcc
	v_cndmask_b32_dpp v108, v112, v108, vcc row_ror:8 row_mask:0xf bank_mask:0xf
	v_cndmask_b32_dpp v109, v113, v109, vcc row_ror:8 row_mask:0xf bank_mask:0xf
	v_cndmask_b32_dpp v110, v114, v110, vcc row_ror:8 row_mask:0xf bank_mask:0xf
	v_cndmask_b32_dpp v111, v115, v111, vcc row_ror:8 row_mask:0xf bank_mask:0xf
	s_not_b64 vcc, vcc
	v_pk_mul_f32 v[112:113], v[132:133], v[232:233]
	v_pk_mul_f32 v[114:115], v[134:135], v[234:235]
	v_pk_mul_f32 v[108:109], v[132:133], v[108:109]
	v_pk_mul_f32 v[110:111], v[134:135], v[110:111]
	global_store_dwordx4 v162, v[112:115], s[30:31]
	global_store_dwordx4 v163, v[108:111], s[30:31]
	v_cndmask_b32_dpp v232, v100, v104, vcc row_ror:8 row_mask:0xf bank_mask:0xf
	v_cndmask_b32_dpp v233, v101, v105, vcc row_ror:8 row_mask:0xf bank_mask:0xf
	v_cndmask_b32_dpp v234, v102, v106, vcc row_ror:8 row_mask:0xf bank_mask:0xf
	v_cndmask_b32_dpp v235, v103, v107, vcc row_ror:8 row_mask:0xf bank_mask:0xf
	s_not_b64 vcc, vcc
	v_cndmask_b32_dpp v100, v104, v100, vcc row_ror:8 row_mask:0xf bank_mask:0xf
	v_cndmask_b32_dpp v101, v105, v101, vcc row_ror:8 row_mask:0xf bank_mask:0xf
	v_cndmask_b32_dpp v102, v106, v102, vcc row_ror:8 row_mask:0xf bank_mask:0xf
	v_cndmask_b32_dpp v103, v107, v103, vcc row_ror:8 row_mask:0xf bank_mask:0xf
	s_not_b64 vcc, vcc
	v_pk_mul_f32 v[104:105], v[140:141], v[232:233]
	v_pk_mul_f32 v[106:107], v[142:143], v[234:235]
	v_pk_mul_f32 v[100:101], v[140:141], v[100:101]
	v_pk_mul_f32 v[102:103], v[142:143], v[102:103]
	global_store_dwordx4 v162, v[104:107], s[30:31] offset:512
	global_store_dwordx4 v163, v[100:103], s[30:31] offset:512
	s_add_u32 s30, s30, 0x10000
	s_addc_u32 s31, s31, 0
	v_cndmask_b32_dpp v232, v92, v96, vcc row_ror:8 row_mask:0xf bank_mask:0xf
	v_cndmask_b32_dpp v233, v93, v97, vcc row_ror:8 row_mask:0xf bank_mask:0xf
	v_cndmask_b32_dpp v234, v94, v98, vcc row_ror:8 row_mask:0xf bank_mask:0xf
	v_cndmask_b32_dpp v235, v95, v99, vcc row_ror:8 row_mask:0xf bank_mask:0xf
	s_not_b64 vcc, vcc
	v_cndmask_b32_dpp v92, v96, v92, vcc row_ror:8 row_mask:0xf bank_mask:0xf
	v_cndmask_b32_dpp v93, v97, v93, vcc row_ror:8 row_mask:0xf bank_mask:0xf
	v_cndmask_b32_dpp v94, v98, v94, vcc row_ror:8 row_mask:0xf bank_mask:0xf
	v_cndmask_b32_dpp v95, v99, v95, vcc row_ror:8 row_mask:0xf bank_mask:0xf
	s_not_b64 vcc, vcc
	v_pk_mul_f32 v[96:97], v[132:133], v[232:233]
	v_pk_mul_f32 v[98:99], v[134:135], v[234:235]
	v_pk_mul_f32 v[92:93], v[132:133], v[92:93]
	v_pk_mul_f32 v[94:95], v[134:135], v[94:95]
	global_store_dwordx4 v162, v[96:99], s[30:31]
	global_store_dwordx4 v163, v[92:95], s[30:31]
	v_cndmask_b32_dpp v232, v84, v88, vcc row_ror:8 row_mask:0xf bank_mask:0xf
	v_cndmask_b32_dpp v233, v85, v89, vcc row_ror:8 row_mask:0xf bank_mask:0xf
	v_cndmask_b32_dpp v234, v86, v90, vcc row_ror:8 row_mask:0xf bank_mask:0xf
	v_cndmask_b32_dpp v235, v87, v91, vcc row_ror:8 row_mask:0xf bank_mask:0xf
	s_not_b64 vcc, vcc
	v_cndmask_b32_dpp v84, v88, v84, vcc row_ror:8 row_mask:0xf bank_mask:0xf
	v_cndmask_b32_dpp v85, v89, v85, vcc row_ror:8 row_mask:0xf bank_mask:0xf
	v_cndmask_b32_dpp v86, v90, v86, vcc row_ror:8 row_mask:0xf bank_mask:0xf
	v_cndmask_b32_dpp v87, v91, v87, vcc row_ror:8 row_mask:0xf bank_mask:0xf
	s_not_b64 vcc, vcc
	v_pk_mul_f32 v[88:89], v[140:141], v[232:233]
	v_pk_mul_f32 v[90:91], v[142:143], v[234:235]
	v_pk_mul_f32 v[84:85], v[140:141], v[84:85]
	v_pk_mul_f32 v[86:87], v[142:143], v[86:87]
	global_store_dwordx4 v162, v[88:91], s[30:31] offset:512
	global_store_dwordx4 v163, v[84:87], s[30:31] offset:512
	s_add_u32 s30, s30, 0x10000
	s_addc_u32 s31, s31, 0
	v_cndmask_b32_dpp v232, v76, v80, vcc row_ror:8 row_mask:0xf bank_mask:0xf
	v_cndmask_b32_dpp v233, v77, v81, vcc row_ror:8 row_mask:0xf bank_mask:0xf
	v_cndmask_b32_dpp v234, v78, v82, vcc row_ror:8 row_mask:0xf bank_mask:0xf
	v_cndmask_b32_dpp v235, v79, v83, vcc row_ror:8 row_mask:0xf bank_mask:0xf
	s_not_b64 vcc, vcc
	v_cndmask_b32_dpp v76, v80, v76, vcc row_ror:8 row_mask:0xf bank_mask:0xf
	v_cndmask_b32_dpp v77, v81, v77, vcc row_ror:8 row_mask:0xf bank_mask:0xf
	v_cndmask_b32_dpp v78, v82, v78, vcc row_ror:8 row_mask:0xf bank_mask:0xf
	v_cndmask_b32_dpp v79, v83, v79, vcc row_ror:8 row_mask:0xf bank_mask:0xf
	s_not_b64 vcc, vcc
	v_pk_mul_f32 v[80:81], v[132:133], v[232:233]
	v_pk_mul_f32 v[82:83], v[134:135], v[234:235]
	v_pk_mul_f32 v[76:77], v[132:133], v[76:77]
	v_pk_mul_f32 v[78:79], v[134:135], v[78:79]
	global_store_dwordx4 v162, v[80:83], s[30:31]
	global_store_dwordx4 v163, v[76:79], s[30:31]
	v_cndmask_b32_dpp v232, v68, v72, vcc row_ror:8 row_mask:0xf bank_mask:0xf
	v_cndmask_b32_dpp v233, v69, v73, vcc row_ror:8 row_mask:0xf bank_mask:0xf
	v_cndmask_b32_dpp v234, v70, v74, vcc row_ror:8 row_mask:0xf bank_mask:0xf
	v_cndmask_b32_dpp v235, v71, v75, vcc row_ror:8 row_mask:0xf bank_mask:0xf
	s_not_b64 vcc, vcc
	v_cndmask_b32_dpp v68, v72, v68, vcc row_ror:8 row_mask:0xf bank_mask:0xf
	v_cndmask_b32_dpp v69, v73, v69, vcc row_ror:8 row_mask:0xf bank_mask:0xf
	v_cndmask_b32_dpp v70, v74, v70, vcc row_ror:8 row_mask:0xf bank_mask:0xf
	v_cndmask_b32_dpp v71, v75, v71, vcc row_ror:8 row_mask:0xf bank_mask:0xf
	s_not_b64 vcc, vcc
	v_pk_mul_f32 v[72:73], v[140:141], v[232:233]
	v_pk_mul_f32 v[74:75], v[142:143], v[234:235]
	v_pk_mul_f32 v[68:69], v[140:141], v[68:69]
	v_pk_mul_f32 v[70:71], v[142:143], v[70:71]
	global_store_dwordx4 v162, v[72:75], s[30:31] offset:512
	global_store_dwordx4 v163, v[68:71], s[30:31] offset:512
	s_add_u32 s30, s30, 0x50000
	s_addc_u32 s31, s31, 0
	v_cndmask_b32_dpp v232, v58, v62, vcc row_ror:8 row_mask:0xf bank_mask:0xf
	v_cndmask_b32_dpp v233, v59, v63, vcc row_ror:8 row_mask:0xf bank_mask:0xf
	v_cndmask_b32_dpp v234, v60, v64, vcc row_ror:8 row_mask:0xf bank_mask:0xf
	v_cndmask_b32_dpp v235, v61, v65, vcc row_ror:8 row_mask:0xf bank_mask:0xf
	s_not_b64 vcc, vcc
	v_cndmask_b32_dpp v58, v62, v58, vcc row_ror:8 row_mask:0xf bank_mask:0xf
	v_cndmask_b32_dpp v59, v63, v59, vcc row_ror:8 row_mask:0xf bank_mask:0xf
	v_cndmask_b32_dpp v60, v64, v60, vcc row_ror:8 row_mask:0xf bank_mask:0xf
	v_cndmask_b32_dpp v61, v65, v61, vcc row_ror:8 row_mask:0xf bank_mask:0xf
	s_not_b64 vcc, vcc
	v_pk_mul_f32 v[62:63], v[132:133], v[232:233]
	v_pk_mul_f32 v[64:65], v[134:135], v[234:235]
	v_pk_mul_f32 v[58:59], v[132:133], v[58:59]
	v_pk_mul_f32 v[60:61], v[134:135], v[60:61]
	global_store_dwordx4 v162, v[62:65], s[30:31]
	global_store_dwordx4 v163, v[58:61], s[30:31]
	v_cndmask_b32_dpp v232, v50, v54, vcc row_ror:8 row_mask:0xf bank_mask:0xf
	v_cndmask_b32_dpp v233, v51, v55, vcc row_ror:8 row_mask:0xf bank_mask:0xf
	v_cndmask_b32_dpp v234, v52, v56, vcc row_ror:8 row_mask:0xf bank_mask:0xf
	v_cndmask_b32_dpp v235, v53, v57, vcc row_ror:8 row_mask:0xf bank_mask:0xf
	s_not_b64 vcc, vcc
	v_cndmask_b32_dpp v50, v54, v50, vcc row_ror:8 row_mask:0xf bank_mask:0xf
	v_cndmask_b32_dpp v51, v55, v51, vcc row_ror:8 row_mask:0xf bank_mask:0xf
	v_cndmask_b32_dpp v52, v56, v52, vcc row_ror:8 row_mask:0xf bank_mask:0xf
	v_cndmask_b32_dpp v53, v57, v53, vcc row_ror:8 row_mask:0xf bank_mask:0xf
	s_not_b64 vcc, vcc
	v_pk_mul_f32 v[54:55], v[140:141], v[232:233]
	v_pk_mul_f32 v[56:57], v[142:143], v[234:235]
	v_pk_mul_f32 v[50:51], v[140:141], v[50:51]
	v_pk_mul_f32 v[52:53], v[142:143], v[52:53]
	global_store_dwordx4 v162, v[54:57], s[30:31] offset:512
	global_store_dwordx4 v163, v[50:53], s[30:31] offset:512
	s_add_u32 s30, s30, 0x10000
	s_addc_u32 s31, s31, 0
	v_cndmask_b32_dpp v232, v42, v46, vcc row_ror:8 row_mask:0xf bank_mask:0xf
	v_cndmask_b32_dpp v233, v43, v47, vcc row_ror:8 row_mask:0xf bank_mask:0xf
	v_cndmask_b32_dpp v234, v44, v48, vcc row_ror:8 row_mask:0xf bank_mask:0xf
	v_cndmask_b32_dpp v235, v45, v49, vcc row_ror:8 row_mask:0xf bank_mask:0xf
	s_not_b64 vcc, vcc
	v_cndmask_b32_dpp v42, v46, v42, vcc row_ror:8 row_mask:0xf bank_mask:0xf
	v_cndmask_b32_dpp v43, v47, v43, vcc row_ror:8 row_mask:0xf bank_mask:0xf
	v_cndmask_b32_dpp v44, v48, v44, vcc row_ror:8 row_mask:0xf bank_mask:0xf
	v_cndmask_b32_dpp v45, v49, v45, vcc row_ror:8 row_mask:0xf bank_mask:0xf
	s_not_b64 vcc, vcc
	v_pk_mul_f32 v[46:47], v[132:133], v[232:233]
	v_pk_mul_f32 v[48:49], v[134:135], v[234:235]
	v_pk_mul_f32 v[42:43], v[132:133], v[42:43]
	v_pk_mul_f32 v[44:45], v[134:135], v[44:45]
	global_store_dwordx4 v162, v[46:49], s[30:31]
	global_store_dwordx4 v163, v[42:45], s[30:31]
	v_cndmask_b32_dpp v232, v34, v38, vcc row_ror:8 row_mask:0xf bank_mask:0xf
	v_cndmask_b32_dpp v233, v35, v39, vcc row_ror:8 row_mask:0xf bank_mask:0xf
	v_cndmask_b32_dpp v234, v36, v40, vcc row_ror:8 row_mask:0xf bank_mask:0xf
	v_cndmask_b32_dpp v235, v37, v41, vcc row_ror:8 row_mask:0xf bank_mask:0xf
	s_not_b64 vcc, vcc
	v_cndmask_b32_dpp v34, v38, v34, vcc row_ror:8 row_mask:0xf bank_mask:0xf
	v_cndmask_b32_dpp v35, v39, v35, vcc row_ror:8 row_mask:0xf bank_mask:0xf
	v_cndmask_b32_dpp v36, v40, v36, vcc row_ror:8 row_mask:0xf bank_mask:0xf
	v_cndmask_b32_dpp v37, v41, v37, vcc row_ror:8 row_mask:0xf bank_mask:0xf
	s_not_b64 vcc, vcc
	v_pk_mul_f32 v[38:39], v[140:141], v[232:233]
	v_pk_mul_f32 v[40:41], v[142:143], v[234:235]
	v_pk_mul_f32 v[34:35], v[140:141], v[34:35]
	v_pk_mul_f32 v[36:37], v[142:143], v[36:37]
	global_store_dwordx4 v162, v[38:41], s[30:31] offset:512
	global_store_dwordx4 v163, v[34:37], s[30:31] offset:512
	s_add_u32 s30, s30, 0x10000
	s_addc_u32 s31, s31, 0
	v_cndmask_b32_dpp v232, v26, v30, vcc row_ror:8 row_mask:0xf bank_mask:0xf
	v_cndmask_b32_dpp v233, v27, v31, vcc row_ror:8 row_mask:0xf bank_mask:0xf
	v_cndmask_b32_dpp v234, v28, v32, vcc row_ror:8 row_mask:0xf bank_mask:0xf
	v_cndmask_b32_dpp v235, v29, v33, vcc row_ror:8 row_mask:0xf bank_mask:0xf
	s_not_b64 vcc, vcc
	v_cndmask_b32_dpp v26, v30, v26, vcc row_ror:8 row_mask:0xf bank_mask:0xf
	v_cndmask_b32_dpp v27, v31, v27, vcc row_ror:8 row_mask:0xf bank_mask:0xf
	v_cndmask_b32_dpp v28, v32, v28, vcc row_ror:8 row_mask:0xf bank_mask:0xf
	v_cndmask_b32_dpp v29, v33, v29, vcc row_ror:8 row_mask:0xf bank_mask:0xf
	s_not_b64 vcc, vcc
	v_pk_mul_f32 v[30:31], v[132:133], v[232:233]
	v_pk_mul_f32 v[32:33], v[134:135], v[234:235]
	v_pk_mul_f32 v[26:27], v[132:133], v[26:27]
	v_pk_mul_f32 v[28:29], v[134:135], v[28:29]
	global_store_dwordx4 v162, v[30:33], s[30:31]
	global_store_dwordx4 v163, v[26:29], s[30:31]
	v_cndmask_b32_dpp v232, v18, v22, vcc row_ror:8 row_mask:0xf bank_mask:0xf
	v_cndmask_b32_dpp v233, v19, v23, vcc row_ror:8 row_mask:0xf bank_mask:0xf
	v_cndmask_b32_dpp v234, v20, v24, vcc row_ror:8 row_mask:0xf bank_mask:0xf
	v_cndmask_b32_dpp v235, v21, v25, vcc row_ror:8 row_mask:0xf bank_mask:0xf
	s_not_b64 vcc, vcc
	v_cndmask_b32_dpp v18, v22, v18, vcc row_ror:8 row_mask:0xf bank_mask:0xf
	v_cndmask_b32_dpp v19, v23, v19, vcc row_ror:8 row_mask:0xf bank_mask:0xf
	v_cndmask_b32_dpp v20, v24, v20, vcc row_ror:8 row_mask:0xf bank_mask:0xf
	v_cndmask_b32_dpp v21, v25, v21, vcc row_ror:8 row_mask:0xf bank_mask:0xf
	s_not_b64 vcc, vcc
	v_pk_mul_f32 v[22:23], v[140:141], v[232:233]
	v_pk_mul_f32 v[24:25], v[142:143], v[234:235]
	v_pk_mul_f32 v[18:19], v[140:141], v[18:19]
	v_pk_mul_f32 v[20:21], v[142:143], v[20:21]
	global_store_dwordx4 v162, v[22:25], s[30:31] offset:512
	global_store_dwordx4 v163, v[18:21], s[30:31] offset:512
	s_add_u32 s30, s30, 0x10000
	s_addc_u32 s31, s31, 0
	v_cndmask_b32_dpp v232, v10, v14, vcc row_ror:8 row_mask:0xf bank_mask:0xf
	v_cndmask_b32_dpp v233, v11, v15, vcc row_ror:8 row_mask:0xf bank_mask:0xf
	v_cndmask_b32_dpp v234, v12, v16, vcc row_ror:8 row_mask:0xf bank_mask:0xf
	v_cndmask_b32_dpp v235, v13, v17, vcc row_ror:8 row_mask:0xf bank_mask:0xf
	s_not_b64 vcc, vcc
	v_cndmask_b32_dpp v10, v14, v10, vcc row_ror:8 row_mask:0xf bank_mask:0xf
	v_cndmask_b32_dpp v11, v15, v11, vcc row_ror:8 row_mask:0xf bank_mask:0xf
	v_cndmask_b32_dpp v12, v16, v12, vcc row_ror:8 row_mask:0xf bank_mask:0xf
	v_cndmask_b32_dpp v13, v17, v13, vcc row_ror:8 row_mask:0xf bank_mask:0xf
	s_not_b64 vcc, vcc
	v_pk_mul_f32 v[14:15], v[132:133], v[232:233]
	v_pk_mul_f32 v[16:17], v[134:135], v[234:235]
	v_pk_mul_f32 v[10:11], v[132:133], v[10:11]
	v_pk_mul_f32 v[12:13], v[134:135], v[12:13]
	global_store_dwordx4 v162, v[14:17], s[30:31]
	global_store_dwordx4 v163, v[10:13], s[30:31]
	v_cndmask_b32_dpp v232, v2, v6, vcc row_ror:8 row_mask:0xf bank_mask:0xf
	v_cndmask_b32_dpp v233, v3, v7, vcc row_ror:8 row_mask:0xf bank_mask:0xf
	v_cndmask_b32_dpp v234, v4, v8, vcc row_ror:8 row_mask:0xf bank_mask:0xf
	v_cndmask_b32_dpp v235, v5, v9, vcc row_ror:8 row_mask:0xf bank_mask:0xf
	s_not_b64 vcc, vcc
	v_cndmask_b32_dpp v2, v6, v2, vcc row_ror:8 row_mask:0xf bank_mask:0xf
	v_cndmask_b32_dpp v3, v7, v3, vcc row_ror:8 row_mask:0xf bank_mask:0xf
	v_cndmask_b32_dpp v4, v8, v4, vcc row_ror:8 row_mask:0xf bank_mask:0xf
	v_cndmask_b32_dpp v5, v9, v5, vcc row_ror:8 row_mask:0xf bank_mask:0xf
	s_not_b64 vcc, vcc
	v_pk_mul_f32 v[6:7], v[140:141], v[232:233]
	v_pk_mul_f32 v[8:9], v[142:143], v[234:235]
	v_pk_mul_f32 v[2:3], v[140:141], v[2:3]
	v_pk_mul_f32 v[4:5], v[142:143], v[4:5]
	global_store_dwordx4 v162, v[6:9], s[30:31] offset:512
	global_store_dwordx4 v163, v[2:5], s[30:31] offset:512
